# memory-key normalisation: gains load hoisted, DPP row-op wave sums instead of bpermute hops
# baseline (speedup 1.0000x reference)
.LBB0_233:
	v_ashrrev_i32_e32 v12, 12, v1
	v_ashrrev_i32_e32 v13, 31, v12
	v_readlane_b32 s0, v250, 61
	v_lshlrev_b64 v[22:23], 21, v[12:13]
	v_readlane_b32 s1, v250, 62
	v_lshlrev_b32_e32 v7, 9, v1
	v_and_b32_e32 v26, 0x1ff800, v7
	v_lshl_add_u64 v[24:25], s[0:1], 0, v[22:23]
	v_mov_b32_e32 v27, v0
	v_lshl_add_u64 v[24:25], v[24:25], 0, v[26:27]
	v_mov_b32_e32 v7, v0
	v_lshl_add_u64 v[24:25], v[24:25], 0, v[6:7]
	v_mov_b32_e32 v9, v0
	v_lshl_add_u64 v[24:25], v[24:25], 0, v[8:9]
	global_load_dwordx2 v[24:25], v[24:25], off
	v_lshlrev_b32_e32 v44, 8, v12
	v_ashrrev_i32_e32 v45, 31, v44
	v_lshl_add_u64 v[44:45], v[44:45], 2, v[2:3]
	global_load_dwordx4 v[40:43], v[44:45], off
	v_lshrrev_b32_e32 v7, 8, v1
	v_and_b32_e32 v7, 12, v7
	v_or_b32_e32 v9, v7, v4
	s_waitcnt lgkmcnt(0)
	v_lshrrev_b32_e32 v11, 3, v1
	v_lshlrev_b32_e32 v9, 7, v9
	v_and_b32_e32 v11, 0x70, v11
	v_readlane_b32 s0, v250, 63
	v_or3_b32 v9, v9, v11, v20
	v_readlane_b32 s1, v249, 0
	v_lshlrev_b32_e32 v9, 6, v9
	v_bfe_u32 v11, v1, 2, 5
	v_lshl_add_u64 v[22:23], s[0:1], 0, v[22:23]
	v_or3_b32 v30, v9, v19, v11
	v_mov_b32_e32 v31, v0
	v_lshl_add_u64 v[22:23], v[30:31], 4, v[22:23]
	v_mov_b32_e32 v11, v0
	v_lshl_add_u64 v[30:31], v[22:23], 0, v[10:11]
	s_waitcnt vmcnt(1)
	v_lshlrev_b32_e32 v26, 16, v24
	v_and_b32_e32 v27, 0xffff0000, v24
	v_lshlrev_b32_e32 v28, 16, v25
	v_and_b32_e32 v29, 0xffff0000, v25
	v_pk_mul_f32 v[34:35], v[26:27], v[26:27]
	v_pk_mul_f32 v[32:33], v[28:29], v[28:29]
	v_add_f32_e32 v9, v34, v35
	v_add_f32_e32 v9, v9, v32
	v_add_f32_e32 v9, v33, v9
	s_nop 1
	v_add_f32_dpp v9, v9, v9 quad_perm:[1,0,3,2] row_mask:0xf bank_mask:0xf
	s_nop 1
	v_add_f32_dpp v9, v9, v9 quad_perm:[2,3,0,1] row_mask:0xf bank_mask:0xf
	s_nop 1
	v_add_f32_dpp v9, v9, v9 row_half_mirror row_mask:0xf bank_mask:0xf
	s_nop 1
	v_add_f32_dpp v9, v9, v9 row_mirror row_mask:0xf bank_mask:0xf
	s_nop 1
	v_add_f32_dpp v9, v9, v9 row_bcast:15 row_mask:0xa bank_mask:0xf
	s_nop 1
	v_add_f32_dpp v9, v9, v9 row_bcast:31 row_mask:0xc bank_mask:0xf
	s_nop 0
	v_readlane_b32 s0, v9, 63
	s_nop 1
	v_mov_b32_e32 v9, s0
	v_fmamk_f32 v9, v9, 0x3b800000, v221
	v_rsq_f32_e32 v32, v9
	s_nop 0
	v_pk_mul_f32 v[26:27], v[32:33], v[26:27] op_sel_hi:[0,1]
	s_waitcnt vmcnt(0)
	v_pk_mul_f32 v[22:23], v[40:41], v[26:27]
	s_nop 0
	v_cvt_pk_bf16_f32 v22, v22, v23
	v_pk_mul_f32 v[26:27], v[32:33], v[28:29] op_sel_hi:[0,1]
	v_pk_mul_f32 v[24:25], v[42:43], v[26:27]
	v_and_b32_e32 v11, 0xffff0000, v22
	v_cvt_pk_bf16_f32 v23, v24, v25
	v_lshlrev_b32_e32 v9, 16, v22
	v_mul_f32_e32 v11, v11, v11
	v_fmac_f32_e32 v11, v9, v9
	v_lshlrev_b32_e32 v9, 16, v23
	v_fmac_f32_e32 v11, v9, v9
	v_and_b32_e32 v9, 0xffff0000, v23
	v_fmac_f32_e32 v11, v9, v9
	global_store_dwordx2 v[30:31], v[22:23], off
	s_nop 1
	v_add_f32_dpp v11, v11, v11 quad_perm:[1,0,3,2] row_mask:0xf bank_mask:0xf
	s_nop 1
	v_add_f32_dpp v11, v11, v11 quad_perm:[2,3,0,1] row_mask:0xf bank_mask:0xf
	s_nop 1
	v_add_f32_dpp v11, v11, v11 row_half_mirror row_mask:0xf bank_mask:0xf
	s_nop 1
	v_add_f32_dpp v11, v11, v11 row_mirror row_mask:0xf bank_mask:0xf
	s_nop 1
	v_add_f32_dpp v11, v11, v11 row_bcast:15 row_mask:0xa bank_mask:0xf
	s_nop 1
	v_add_f32_dpp v11, v11, v11 row_bcast:31 row_mask:0xc bank_mask:0xf
	s_and_saveexec_b64 s[34:35], vcc
	s_cbranch_execz .LBB0_232
	v_lshlrev_b32_e32 v12, 4, v12
	v_readlane_b32 s0, v249, 1
	v_ashrrev_i32_e32 v13, 31, v12
	v_readlane_b32 s1, v249, 2
	v_lshlrev_b32_e32 v22, 2, v7
	v_mov_b32_e32 v23, v0
	v_lshl_add_u64 v[12:13], v[12:13], 2, s[0:1]
	v_lshl_add_u64 v[12:13], v[12:13], 0, v[22:23]
	v_lshlrev_b32_e32 v22, 2, v4
	v_readlane_b32 s0, v11, 63
	s_nop 1
	v_mov_b32_e32 v9, s0
	v_lshl_add_u64 v[12:13], v[12:13], 0, v[22:23]
	global_atomic_umax v[12:13], v9, off
	s_branch .LBB0_232
